# attention tile loops: xor-32 exchange of the running row maximum via v_permlane32_swap (3 VALU) instead of ds_bpermute + LDS wait
# speedup vs baseline: 1.0000x; 1.0000x over previous
.LBB0_908:
	s_nop 10
	v_max_f32_e32 v159, v65, v65
	v_max_f32_e32 v194, v81, v81
	v_max_f32_e32 v159, v194, v159
	v_max_f32_e32 v194, v66, v66
	v_max_f32_e32 v195, v82, v82
	v_max_f32_e32 v194, v195, v194
	v_max_f32_e32 v195, v67, v67
	v_max_f32_e32 v196, v83, v83
	v_max3_f32 v159, v80, v64, v159
	v_max_f32_e32 v195, v196, v195
	v_max3_f32 v159, v159, v194, v195
	v_max_f32_e32 v194, v68, v68
	v_max_f32_e32 v195, v84, v84
	v_max_f32_e32 v194, v195, v194
	v_max_f32_e32 v195, v69, v69
	v_max_f32_e32 v196, v85, v85
	v_max_f32_e32 v195, v196, v195
	v_max3_f32 v159, v159, v194, v195
	v_max_f32_e32 v194, v70, v70
	v_max_f32_e32 v195, v86, v86
	v_max_f32_e32 v194, v195, v194
	v_max_f32_e32 v195, v71, v71
	v_max_f32_e32 v196, v87, v87
	v_max_f32_e32 v195, v196, v195
	v_max3_f32 v159, v159, v194, v195
	v_max_f32_e32 v194, v72, v72
	v_max_f32_e32 v195, v88, v88
	v_max_f32_e32 v194, v195, v194
	v_max_f32_e32 v195, v73, v73
	v_max_f32_e32 v196, v89, v89
	v_max_f32_e32 v195, v196, v195
	v_max3_f32 v159, v159, v194, v195
	v_max_f32_e32 v194, v74, v74
	v_max_f32_e32 v195, v90, v90
	v_max_f32_e32 v194, v195, v194
	v_max_f32_e32 v195, v75, v75
	v_max_f32_e32 v196, v91, v91
	v_max_f32_e32 v195, v196, v195
	v_max3_f32 v159, v159, v194, v195
	v_max_f32_e32 v194, v76, v76
	v_max_f32_e32 v195, v92, v92
	v_max_f32_e32 v194, v195, v194
	v_max_f32_e32 v195, v77, v77
	v_max_f32_e32 v196, v93, v93
	v_max_f32_e32 v195, v196, v195
	v_max3_f32 v159, v159, v194, v195
	v_max_f32_e32 v194, v78, v78
	v_max_f32_e32 v195, v94, v94
	v_max_f32_e32 v194, v195, v194
	v_max_f32_e32 v195, v79, v79
	v_max_f32_e32 v196, v95, v95
	v_max_f32_e32 v195, v196, v195
	v_max3_f32 v159, v159, v194, v195
	v_mov_b32_e32 v194, v159
	s_nop 1
	v_permlane32_swap_b32 v194, v159
	s_waitcnt lgkmcnt(0)
	v_max3_f32 v159, v193, v159, v194
	v_sub_f32_e32 v193, v193, v159
	v_exp_f32_e32 v193, v193
	s_nop 0
	v_cmp_neq_f32_e32 vcc, 1.0, v193
	s_cbranch_vccz .LBB0_912
	s_and_saveexec_b64 s[18:19], s[0:1]
	ds_write_b32 v186, v193 offset:35840
	s_or_b64 exec, exec, s[18:19]
	s_waitcnt lgkmcnt(0)
	v_add_u32_e32 v206, s6, v210
	ds_read_b128 v[194:197], v206 offset:35936
	ds_read_b128 v[198:201], v206 offset:35904
	ds_read_b128 v[202:205], v206 offset:35872
	ds_read_b128 v[206:209], v206 offset:35840
	s_waitcnt lgkmcnt(3)
	v_pk_mul_f32 v[44:45], v[44:45], v[194:195]
	s_waitcnt lgkmcnt(2)
	v_pk_mul_f32 v[40:41], v[40:41], v[198:199]
	s_waitcnt lgkmcnt(1)
	v_pk_mul_f32 v[36:37], v[36:37], v[202:203]
	v_pk_mul_f32 v[46:47], v[46:47], v[196:197]
	v_pk_mul_f32 v[42:43], v[42:43], v[200:201]
	v_pk_mul_f32 v[38:39], v[38:39], v[204:205]
	s_waitcnt lgkmcnt(0)
	v_pk_mul_f32 v[34:35], v[34:35], v[208:209]
	v_pk_mul_f32 v[32:33], v[32:33], v[206:207]
	v_pk_mul_f32 v[60:61], v[60:61], v[194:195]
	v_pk_mul_f32 v[56:57], v[56:57], v[198:199]
	v_pk_mul_f32 v[52:53], v[52:53], v[202:203]
	v_pk_mul_f32 v[62:63], v[62:63], v[196:197]
	v_pk_mul_f32 v[58:59], v[58:59], v[200:201]
	v_pk_mul_f32 v[54:55], v[54:55], v[204:205]
	v_pk_mul_f32 v[50:51], v[50:51], v[208:209]
	v_pk_mul_f32 v[48:49], v[48:49], v[206:207]
	v_pk_mul_f32 v[28:29], v[28:29], v[194:195]
	v_pk_mul_f32 v[24:25], v[24:25], v[198:199]
	v_pk_mul_f32 v[20:21], v[20:21], v[202:203]
	v_pk_mul_f32 v[30:31], v[30:31], v[196:197]
	v_pk_mul_f32 v[26:27], v[26:27], v[200:201]
	v_pk_mul_f32 v[22:23], v[22:23], v[204:205]
	v_pk_mul_f32 v[18:19], v[18:19], v[208:209]
	v_pk_mul_f32 v[16:17], v[16:17], v[206:207]
	v_pk_mul_f32 v[12:13], v[12:13], v[194:195]
	v_pk_mul_f32 v[8:9], v[8:9], v[198:199]
	v_pk_mul_f32 v[4:5], v[4:5], v[202:203]
	v_pk_mul_f32 v[14:15], v[14:15], v[196:197]
	v_pk_mul_f32 v[10:11], v[10:11], v[200:201]
	v_pk_mul_f32 v[6:7], v[6:7], v[204:205]
	v_pk_mul_f32 v[2:3], v[2:3], v[208:209]
	v_pk_mul_f32 v[0:1], v[0:1], v[206:207]

.LBB0_947:
	s_nop 10
	v_max_f32_e32 v157, v65, v65
	v_max_f32_e32 v192, v81, v81
	v_max_f32_e32 v157, v192, v157
	v_max_f32_e32 v192, v66, v66
	v_max_f32_e32 v193, v82, v82
	v_max_f32_e32 v192, v193, v192
	v_max_f32_e32 v193, v67, v67
	v_max_f32_e32 v194, v83, v83
	v_max3_f32 v157, v80, v64, v157
	v_max_f32_e32 v193, v194, v193
	v_max3_f32 v157, v157, v192, v193
	v_max_f32_e32 v192, v68, v68
	v_max_f32_e32 v193, v84, v84
	v_max_f32_e32 v192, v193, v192
	v_max_f32_e32 v193, v69, v69
	v_max_f32_e32 v194, v85, v85
	v_max_f32_e32 v193, v194, v193
	v_max3_f32 v157, v157, v192, v193
	v_max_f32_e32 v192, v70, v70
	v_max_f32_e32 v193, v86, v86
	v_max_f32_e32 v192, v193, v192
	v_max_f32_e32 v193, v71, v71
	v_max_f32_e32 v194, v87, v87
	v_max_f32_e32 v193, v194, v193
	v_max3_f32 v157, v157, v192, v193
	v_max_f32_e32 v192, v72, v72
	v_max_f32_e32 v193, v88, v88
	v_max_f32_e32 v192, v193, v192
	v_max_f32_e32 v193, v73, v73
	v_max_f32_e32 v194, v89, v89
	v_max_f32_e32 v193, v194, v193
	v_max3_f32 v157, v157, v192, v193
	v_max_f32_e32 v192, v74, v74
	v_max_f32_e32 v193, v90, v90
	v_max_f32_e32 v192, v193, v192
	v_max_f32_e32 v193, v75, v75
	v_max_f32_e32 v194, v91, v91
	v_max_f32_e32 v193, v194, v193
	v_max3_f32 v157, v157, v192, v193
	v_max_f32_e32 v192, v76, v76
	v_max_f32_e32 v193, v92, v92
	v_max_f32_e32 v192, v193, v192
	v_max_f32_e32 v193, v77, v77
	v_max_f32_e32 v194, v93, v93
	v_max_f32_e32 v193, v194, v193
	v_max3_f32 v157, v157, v192, v193
	v_max_f32_e32 v192, v78, v78
	v_max_f32_e32 v193, v94, v94
	v_max_f32_e32 v192, v193, v192
	v_max_f32_e32 v193, v79, v79
	v_max_f32_e32 v194, v95, v95
	v_max_f32_e32 v193, v194, v193
	v_max3_f32 v157, v157, v192, v193
	v_mov_b32_e32 v192, v157
	s_nop 1
	v_permlane32_swap_b32 v192, v157
	s_waitcnt lgkmcnt(0)
	v_max3_f32 v157, v191, v157, v192
	v_sub_f32_e32 v191, v191, v157
	v_exp_f32_e32 v191, v191
	s_nop 0
	v_cmp_neq_f32_e32 vcc, 1.0, v191
	s_cbranch_vccz .LBB0_951
	s_and_saveexec_b64 s[18:19], s[0:1]
	ds_write_b32 v184, v191 offset:35840
	s_or_b64 exec, exec, s[18:19]
	s_waitcnt lgkmcnt(0)
	v_add_u32_e32 v204, s6, v210
	ds_read_b128 v[192:195], v204 offset:35936
	ds_read_b128 v[196:199], v204 offset:35904
	ds_read_b128 v[200:203], v204 offset:35872
	ds_read_b128 v[204:207], v204 offset:35840
	s_waitcnt lgkmcnt(3)
	v_pk_mul_f32 v[44:45], v[44:45], v[192:193]
	s_waitcnt lgkmcnt(2)
	v_pk_mul_f32 v[40:41], v[40:41], v[196:197]
	s_waitcnt lgkmcnt(1)
	v_pk_mul_f32 v[36:37], v[36:37], v[200:201]
	v_pk_mul_f32 v[46:47], v[46:47], v[194:195]
	v_pk_mul_f32 v[42:43], v[42:43], v[198:199]
	v_pk_mul_f32 v[38:39], v[38:39], v[202:203]
	s_waitcnt lgkmcnt(0)
	v_pk_mul_f32 v[34:35], v[34:35], v[206:207]
	v_pk_mul_f32 v[32:33], v[32:33], v[204:205]
	v_pk_mul_f32 v[60:61], v[60:61], v[192:193]
	v_pk_mul_f32 v[56:57], v[56:57], v[196:197]
	v_pk_mul_f32 v[52:53], v[52:53], v[200:201]
	v_pk_mul_f32 v[62:63], v[62:63], v[194:195]
	v_pk_mul_f32 v[58:59], v[58:59], v[198:199]
	v_pk_mul_f32 v[54:55], v[54:55], v[202:203]
	v_pk_mul_f32 v[50:51], v[50:51], v[206:207]
	v_pk_mul_f32 v[48:49], v[48:49], v[204:205]
	v_pk_mul_f32 v[28:29], v[28:29], v[192:193]
	v_pk_mul_f32 v[24:25], v[24:25], v[196:197]
	v_pk_mul_f32 v[20:21], v[20:21], v[200:201]
	v_pk_mul_f32 v[30:31], v[30:31], v[194:195]
	v_pk_mul_f32 v[26:27], v[26:27], v[198:199]
	v_pk_mul_f32 v[22:23], v[22:23], v[202:203]
	v_pk_mul_f32 v[18:19], v[18:19], v[206:207]
	v_pk_mul_f32 v[16:17], v[16:17], v[204:205]
	v_pk_mul_f32 v[12:13], v[12:13], v[192:193]
	v_pk_mul_f32 v[8:9], v[8:9], v[196:197]
	v_pk_mul_f32 v[4:5], v[4:5], v[200:201]
	v_pk_mul_f32 v[14:15], v[14:15], v[194:195]
	v_pk_mul_f32 v[10:11], v[10:11], v[198:199]
	v_pk_mul_f32 v[6:7], v[6:7], v[202:203]
	v_pk_mul_f32 v[2:3], v[2:3], v[206:207]
	v_pk_mul_f32 v[0:1], v[0:1], v[204:205]

.LBB0_1057:
	s_add_i32 s41, s41, 1
	s_cmp_lt_i32 s41, s9
	s_mov_b64 s[24:25], s[12:13]
	s_cselect_b64 s[12:13], -1, 0
	s_cmp_eq_u32 s41, s9
	s_mov_b64 s[26:27], s[16:17]
	s_mov_b32 s44, s8
	s_cselect_b64 s[16:17], -1, 0
	s_min_i32 s8, s41, s9
	s_mul_i32 s8, s8, s92
	s_add_i32 s8, s8, s96
	s_min_i32 s8, s8, 0x9f
	s_ashr_i32 s22, s8, 31
	s_lshr_b32 s22, s22, 29
	s_add_i32 s22, s8, s22
	s_ashr_i32 s23, s22, 3
	s_and_b32 s22, s22, -8
	s_and_b64 s[16:17], s[16:17], s[4:5]
	s_sub_i32 s8, s8, s22
	s_cmp_lt_i32 s8, 0
	s_cselect_b32 s22, 21, 20
	s_mul_i32 s8, s8, s22
	s_add_i32 s8, s8, s23
	s_mul_hi_i32 s22, s8, 0x2aaaaaab
	s_lshr_b32 s23, s22, 31
	s_ashr_i32 s22, s22, 1
	s_add_i32 s22, s22, s23
	s_mul_i32 s28, s22, 3
	s_sub_i32 s23, 40, s28
	s_min_u32 s29, s23, 3
	s_mul_i32 s22, s22, 12
	s_sub_i32 s46, s8, s22
	v_cvt_f32_ubyte0_e32 v1, s29
	v_cvt_f32_i32_e32 v0, s46
	v_rcp_iflag_f32_e32 v2, v1
	s_ashr_i32 s8, s46, 30
	s_or_b32 s8, s8, 1
	s_mov_b32 s45, s34
	v_mul_f32_e32 v2, v0, v2
	v_trunc_f32_e32 v2, v2
	v_fma_f32 v0, -v2, v1, v0
	v_cvt_i32_f32_e32 v2, v2
	v_cmp_ge_f32_e64 s[22:23], |v0|, v1
	s_and_b64 s[22:23], s[22:23], exec
	s_cselect_b32 s8, s8, 0
	v_readfirstlane_b32 s22, v2
	s_add_i32 s8, s22, s8
	s_mul_i32 s22, s8, s29
	s_sub_i32 s22, s46, s22
	s_sext_i32_i8 s22, s22
	s_add_i32 s34, s28, s22
	s_or_b64 s[22:23], s[12:13], s[16:17]
	s_lshl_b32 s12, s34, 8
	s_ashr_i32 s13, s12, 31
	s_lshl_b64 s[12:13], s[12:13], 11
	s_add_u32 s12, s6, s12
	s_addc_u32 s13, s7, s13
	s_and_b64 s[16:17], s[22:23], exec
	s_cselect_b32 s46, s13, s25
	s_cselect_b32 s47, s12, s24
	s_bfe_i64 s[16:17], s[8:9], 0x80000
	s_lshl_b64 s[16:17], s[16:17], 19
	s_add_u32 s16, s30, s16
	s_addc_u32 s17, s31, s17
	s_and_b64 s[28:29], s[22:23], exec
	s_cselect_b32 s48, s17, s27
	s_cselect_b32 s49, s16, s26
	s_add_u32 s24, s24, 0x40080
	s_addc_u32 s25, s25, 0
	s_add_u32 s50, s26, 0x100
	v_mov_b32_e32 v0, 0
	s_addc_u32 s51, s27, 0
	s_mov_b32 s56, -2
	v_mov_b32_e32 v1, v0
	v_mov_b32_e32 v2, v0
	v_mov_b32_e32 v3, v0
	v_mov_b32_e32 v4, v0
	v_mov_b32_e32 v5, v0
	v_mov_b32_e32 v6, v0
	v_mov_b32_e32 v7, v0
	v_mov_b32_e32 v16, v0
	v_mov_b32_e32 v17, v0
	v_mov_b32_e32 v18, v0
	v_mov_b32_e32 v19, v0
	v_mov_b32_e32 v20, v0
	v_mov_b32_e32 v21, v0
	v_mov_b32_e32 v22, v0
	v_mov_b32_e32 v23, v0
	v_mov_b32_e32 v32, v0
	v_mov_b32_e32 v33, v0
	v_mov_b32_e32 v34, v0
	v_mov_b32_e32 v35, v0
	v_mov_b32_e32 v36, v0
	v_mov_b32_e32 v37, v0
	v_mov_b32_e32 v38, v0
	v_mov_b32_e32 v39, v0
	v_mov_b32_e32 v48, v0
	v_mov_b32_e32 v49, v0
	v_mov_b32_e32 v50, v0
	v_mov_b32_e32 v51, v0
	v_mov_b32_e32 v52, v0
	v_mov_b32_e32 v53, v0
	v_mov_b32_e32 v54, v0
	v_mov_b32_e32 v55, v0
	v_mov_b32_e32 v8, v0
	v_mov_b32_e32 v9, v0
	v_mov_b32_e32 v10, v0
	v_mov_b32_e32 v11, v0
	v_mov_b32_e32 v12, v0
	v_mov_b32_e32 v13, v0
	v_mov_b32_e32 v14, v0
	v_mov_b32_e32 v15, v0
	v_mov_b32_e32 v24, v0
	v_mov_b32_e32 v25, v0
	v_mov_b32_e32 v26, v0
	v_mov_b32_e32 v27, v0
	v_mov_b32_e32 v28, v0
	v_mov_b32_e32 v29, v0
	v_mov_b32_e32 v30, v0
	v_mov_b32_e32 v31, v0
	v_mov_b32_e32 v40, v0
	v_mov_b32_e32 v41, v0
	v_mov_b32_e32 v42, v0
	v_mov_b32_e32 v43, v0
	v_mov_b32_e32 v44, v0
	v_mov_b32_e32 v45, v0
	v_mov_b32_e32 v46, v0
	v_mov_b32_e32 v47, v0
	v_mov_b32_e32 v56, v0
	v_mov_b32_e32 v57, v0
	v_mov_b32_e32 v58, v0
	v_mov_b32_e32 v59, v0
	v_mov_b32_e32 v60, v0
	v_mov_b32_e32 v61, v0
	v_mov_b32_e32 v62, v0
	v_mov_b32_e32 v63, v0
	v_mov_b32_e32 v64, v0
	v_mov_b32_e32 v65, v0
	v_mov_b32_e32 v66, v0
	v_mov_b32_e32 v67, v0
	v_mov_b32_e32 v68, v0
	v_mov_b32_e32 v69, v0
	v_mov_b32_e32 v70, v0
	v_mov_b32_e32 v71, v0
	v_mov_b32_e32 v80, v0
	v_mov_b32_e32 v81, v0
	v_mov_b32_e32 v82, v0
	v_mov_b32_e32 v83, v0
	v_mov_b32_e32 v84, v0
	v_mov_b32_e32 v85, v0
	v_mov_b32_e32 v86, v0
	v_mov_b32_e32 v87, v0
	v_mov_b32_e32 v96, v0
	s_waitcnt lgkmcnt(0)
	v_mov_b32_e32 v97, v0
	v_mov_b32_e32 v98, v0
	v_mov_b32_e32 v99, v0
	v_mov_b32_e32 v100, v0
	v_mov_b32_e32 v101, v0
	v_mov_b32_e32 v102, v0
	v_mov_b32_e32 v103, v0
	v_mov_b32_e32 v112, v0
	v_mov_b32_e32 v113, v0
	v_mov_b32_e32 v114, v0
	v_mov_b32_e32 v115, v0
	v_mov_b32_e32 v116, v0
	v_mov_b32_e32 v117, v0
	v_mov_b32_e32 v118, v0
	v_mov_b32_e32 v119, v0
	v_mov_b32_e32 v72, v0
	v_mov_b32_e32 v73, v0
	v_mov_b32_e32 v74, v0
	v_mov_b32_e32 v75, v0
	v_mov_b32_e32 v76, v0
	v_mov_b32_e32 v77, v0
	v_mov_b32_e32 v78, v0
	v_mov_b32_e32 v79, v0
	v_mov_b32_e32 v88, v0
	v_mov_b32_e32 v89, v0
	v_mov_b32_e32 v90, v0
	v_mov_b32_e32 v91, v0
	v_mov_b32_e32 v92, v0
	v_mov_b32_e32 v93, v0
	v_mov_b32_e32 v94, v0
	v_mov_b32_e32 v95, v0
	v_mov_b32_e32 v104, v0
	v_mov_b32_e32 v105, v0
	v_mov_b32_e32 v106, v0
	v_mov_b32_e32 v107, v0
	v_mov_b32_e32 v108, v0
	v_mov_b32_e32 v109, v0
	v_mov_b32_e32 v110, v0
	v_mov_b32_e32 v111, v0
	v_mov_b32_e32 v120, v0
	v_mov_b32_e32 v121, v0
	v_mov_b32_e32 v122, v0
	v_mov_b32_e32 v123, v0
	v_mov_b32_e32 v124, v0
	v_mov_b32_e32 v125, v0
	v_mov_b32_e32 v126, v0
	v_mov_b32_e32 v127, v0
	s_nop 0
	s_nop 0
	s_nop 0
	s_nop 0
	s_nop 0
	s_nop 0
	s_nop 0
	s_nop 0
	s_nop 0
	s_nop 0
	s_nop 0
	s_nop 0
